# ragged-round overlap: workgroups 64..255 arrive at seam 1 right after GEMM1, then run the tail transposes, then wait for the release
# speedup vs baseline: 1.0007x; 1.0007x over previous
; #define LAS __attribute__((address_space(3)))
; __device__ __forceinline__ void own_barrier(unsigned* cnt, unsigned G) {
;     asm volatile("s_waitcnt vmcnt(0) lgkmcnt(0)" ::: "memory");
;     __syncthreads();
;     if (threadIdx.x == 0) {
;         __builtin_amdgcn_fence(__ATOMIC_RELEASE, "agent"); asm volatile("s_waitcnt vmcnt(0)" ::: "memory");
;         unsigned target;
;         if ((G & 7u) == 0u) { target = 8u;
;             const unsigned old = __hip_atomic_fetch_add(cnt + 64 * (1 + (blockIdx.x & 7)), 1u, __ATOMIC_RELAXED, __HIP_MEMORY_SCOPE_AGENT);
;             if (old + 1u == (G >> 3)) __hip_atomic_fetch_add(cnt, 1u, __ATOMIC_RELAXED, __HIP_MEMORY_SCOPE_AGENT); }
;         else { target = G; __hip_atomic_fetch_add(cnt, 1u, __ATOMIC_RELAXED, __HIP_MEMORY_SCOPE_AGENT); }
; __global__ void __launch_bounds__(512, 2) hybrid_fwd(Args a) {
;     ...
;             const int nwg = (M / 256) * (a.n_fp8 > 0 ? a.n_fp8 : a.n_bf16), rem = nwg % G; const int first = rem ? rem : 0, nhelp = G - first;
;             if (bx >= first) {
;                 LAS float* scr = (LAS float*)(lds + wave * 16384);
;                 const int gw = (bx - first) * 8 + wave, NGW = nhelp * 8;
;                 constexpr int I_PA = (1024 / 64) * (D / 32), I_PB = (512 / 64) * (D / 32), I_OUT = (D / 64) * (D / 32);
;                 for (int it = gw; it < I_PA + I_PB + I_OUT; it += NGW) {
;                     int r = it;
;                     if (r < I_PA) { const int nb = r % (D / 32), kb = r / (D / 32); transpose_item_fp8(a.w_pa, D, Wp8, 1536, 0, 64 * kb, 32 * nb, 32 * nb, W8_SCALE, scr, lane); continue; } r -= I_PA;
;                     if (r < I_PB) { const int nb = r % (D / 32), kb = r / (D / 32); transpose_item_fp8(a.w_pb, D, Wp8, 1536, 1024, 64 * kb, 32 * nb, 32 * nb, W8_SCALE, scr, lane); continue; } r -= I_PB;
;                     { const int nb = r % (D / 32), kb = r / (D / 32); transpose_item_fp8(a.w_out, D, Wout8, 2048, 0, 64 * kb, 32 * nb, 32 * nb, W8_SCALE, scr, lane); }
.LBB0_266:
	s_waitcnt vmcnt(0)
	s_barrier
	s_cmp_lg_u32 s101, 1
	s_cbranch_scc1 .Learly_skip
	s_cmp_lt_u32 s2, 64
	s_cbranch_scc1 .Learly_skip
	v_readfirstlane_b32 s100, v160
	s_cmp_lg_u32 s100, 0
	s_cbranch_scc1 .Learly_skip
	s_mov_b64 exec, 1
	buffer_wbl2 sc1
	s_waitcnt vmcnt(0)
	v_mov_b32_e32 v245, 0x8e01000
	v_mov_b32_e32 v244, 1
	global_atomic_add v244, v245, v244, s[90:91] sc0
	s_waitcnt vmcnt(0)
	v_readfirstlane_b32 s100, v244
	s_mov_b64 exec, -1
	s_cmp_eq_u32 s100, 0xff
	s_cbranch_scc0 .Learly_skip
	v_mbcnt_lo_u32_b32 v243, -1, 0
	v_mbcnt_hi_u32_b32 v243, -1, v243
	v_lshlrev_b32_e32 v243, 12, v243
	v_add_u32_e32 v243, 0x8e10000, v243
	v_mov_b32_e32 v244, 1
	global_store_dword v243, v244, s[90:91] sc1
	v_add_u32_e32 v243, 0x40000, v243
	global_store_dword v243, v244, s[90:91] sc1
	v_add_u32_e32 v243, 0x40000, v243
	global_store_dword v243, v244, s[90:91] sc1
	v_add_u32_e32 v243, 0x40000, v243
	global_store_dword v243, v244, s[90:91] sc1
.Learly_skip:
.LBB0_267:
	s_add_u32 s6, s90, 0x6e00000
	s_load_dword s0, s[70:71], 0x1c0
	s_addc_u32 s7, s91, 0
	s_add_u32 s98, s90, 0x7400000
	s_addc_u32 s99, s91, 0
	s_cmp_gt_i32 s46, 0
	s_waitcnt lgkmcnt(0)
	s_cselect_b32 s0, s46, s0
	s_abs_i32 s33, s92
	v_cvt_f32_u32_e32 v0, s33
	s_sub_i32 s4, 0, s33
	s_lshl_b32 s0, s0, 6
	s_ashr_i32 s1, s0, 31
	v_rcp_iflag_f32_e32 v0, v0
	s_abs_i32 s0, s0
	v_mul_f32_e32 v0, 0x4f7ffffe, v0
	v_cvt_u32_f32_e32 v0, v0
	s_nop 0
	v_readfirstlane_b32 s5, v0
	s_mul_i32 s4, s4, s5
	s_mul_hi_u32 s4, s5, s4
	s_add_i32 s4, s5, s4
	v_writelane_b32 v242, s4, 3
	s_mul_hi_u32 s4, s0, s4
	s_mul_i32 s4, s4, s33
	s_sub_i32 s0, s0, s4
	s_sub_i32 s4, s0, s33
	s_cmp_ge_u32 s0, s33
	s_cselect_b32 s0, s4, s0
	s_sub_i32 s4, s0, s33
	s_cmp_ge_u32 s0, s33
	s_cselect_b32 s0, s4, s0
	s_xor_b32 s0, s0, s1
	s_sub_i32 s0, s0, s1
	s_cmp_lt_i32 s2, s0
	s_cbranch_scc1 .LBB0_279
	s_cmp_lg_u32 s101, 1
	s_cbranch_scc1 .Ltail_orig
	s_load_dwordx4 s[12:15], s[70:71], 0x28
	s_load_dwordx2 s[10:11], s[70:71], 0x38
	v_mbcnt_lo_u32_b32 v113, -1, 0
	v_mbcnt_hi_u32_b32 v113, -1, v113
	v_and_b32_e32 v114, 7, v113
	v_lshrrev_b32_e32 v115, 3, v113
	v_lshlrev_b32_e32 v96, 16, v115
	v_lshl_or_b32 v96, v114, 4, v96
	v_add_u32_e32 v97, 0x2000, v96
	v_add_u32_e32 v98, 0x4000, v96
	v_add_u32_e32 v99, 0x6000, v96
	v_add_u32_e32 v100, 0x8000, v96
	v_add_u32_e32 v101, 0xa000, v96
	v_add_u32_e32 v102, 0xc000, v96
	v_add_u32_e32 v103, 0xe000, v96
	v_lshlrev_b32_e32 v104, 2, v114
	v_add_u32_e32 v105, 1, v104
	v_add_u32_e32 v106, 2, v104
	v_add_u32_e32 v107, 3, v104
	v_lshlrev_b32_e32 v108, 3, v115
	v_readfirstlane_b32 s9, v160
	s_lshr_b32 s9, s9, 6
	s_sub_u32 s8, s2, 64
	s_lshl_b32 s8, s8, 3
	s_add_u32 s8, s8, s9
	s_waitcnt lgkmcnt(0)
	s_add_u32 s9, s8, 0x0
	s_sub_u32 s4, s9, 0x400
	s_sub_u32 s5, s9, 0x600
	s_mov_b32 vcc_lo, 0x6e00400
	s_mov_b32 vcc_hi, 0x7400000
	s_cmp_lt_u32 s9, 0x600
	s_cselect_b32 s5, s4, s5
	s_cselect_b32 s0, s14, s10
	s_cselect_b32 s1, s15, s11
	s_cselect_b32 s100, vcc_lo, vcc_hi
	s_movk_i32 s4, 0x600
	s_movk_i32 vcc_lo, 0x800
	s_cselect_b32 s4, s4, vcc_lo
	s_mov_b32 vcc_hi, 0x6e00000
	s_cmp_lt_u32 s9, 0x400
	s_cselect_b32 s5, s9, s5
	s_cselect_b32 s0, s12, s0
	s_cselect_b32 s1, s13, s1
	s_cselect_b32 s100, vcc_hi, s100
	s_lshr_b32 s9, s5, 6
	s_and_b32 s5, s5, 63
	s_lshl_b32 vcc_lo, s9, 19
	s_lshl_b32 vcc_hi, s5, 7
	s_add_u32 vcc_lo, vcc_lo, vcc_hi
	s_add_u32 s0, s0, vcc_lo
	s_addc_u32 s1, s1, 0
	s_lshl_b32 s5, s5, 5
	s_mul_i32 s5, s5, s4
	s_lshl_b32 s9, s9, 6
	s_add_u32 s100, s100, s5
	s_add_u32 s100, s100, s9
	v_mov_b32_e32 v113, s4
	v_mad_u32_u24 v116, v104, v113, v108
	v_mad_u32_u24 v117, v105, v113, v108
	v_mad_u32_u24 v118, v106, v113, v108
	v_mad_u32_u24 v119, v107, v113, v108
	v_add_u32_e32 v116, s100, v116
	v_add_u32_e32 v117, s100, v117
	v_add_u32_e32 v118, s100, v118
	v_add_u32_e32 v119, s100, v119
	global_load_dwordx4 v[0:3], v96, s[0:1] nt
	global_load_dwordx4 v[4:7], v97, s[0:1] nt
	global_load_dwordx4 v[8:11], v98, s[0:1] nt
	global_load_dwordx4 v[12:15], v99, s[0:1] nt
	global_load_dwordx4 v[16:19], v100, s[0:1] nt
	global_load_dwordx4 v[20:23], v101, s[0:1] nt
	global_load_dwordx4 v[24:27], v102, s[0:1] nt
	global_load_dwordx4 v[28:31], v103, s[0:1] nt
	s_add_u32 s9, s8, 0x600
	s_sub_u32 s4, s9, 0x400
	s_sub_u32 s5, s9, 0x600
	s_mov_b32 vcc_lo, 0x6e00400
	s_mov_b32 vcc_hi, 0x7400000
	s_cmp_lt_u32 s9, 0x600
	s_cselect_b32 s5, s4, s5
	s_cselect_b32 s0, s14, s10
	s_cselect_b32 s1, s15, s11
	s_cselect_b32 s100, vcc_lo, vcc_hi
	s_movk_i32 s4, 0x600
	s_movk_i32 vcc_lo, 0x800
	s_cselect_b32 s4, s4, vcc_lo
	s_mov_b32 vcc_hi, 0x6e00000
	s_cmp_lt_u32 s9, 0x400
	s_cselect_b32 s5, s9, s5
	s_cselect_b32 s0, s12, s0
	s_cselect_b32 s1, s13, s1
	s_cselect_b32 s100, vcc_hi, s100
	s_lshr_b32 s9, s5, 6
	s_and_b32 s5, s5, 63
	s_lshl_b32 vcc_lo, s9, 19
	s_lshl_b32 vcc_hi, s5, 7
	s_add_u32 vcc_lo, vcc_lo, vcc_hi
	s_add_u32 s0, s0, vcc_lo
	s_addc_u32 s1, s1, 0
	s_lshl_b32 s5, s5, 5
	s_mul_i32 s5, s5, s4
	s_lshl_b32 s9, s9, 6
	s_add_u32 s100, s100, s5
	s_add_u32 s100, s100, s9
	v_mov_b32_e32 v113, s4
	v_mad_u32_u24 v120, v104, v113, v108
	v_mad_u32_u24 v121, v105, v113, v108
	v_mad_u32_u24 v122, v106, v113, v108
	v_mad_u32_u24 v123, v107, v113, v108
	v_add_u32_e32 v120, s100, v120
	v_add_u32_e32 v121, s100, v121
	v_add_u32_e32 v122, s100, v122
	v_add_u32_e32 v123, s100, v123
	global_load_dwordx4 v[32:35], v96, s[0:1] nt
	global_load_dwordx4 v[36:39], v97, s[0:1] nt
	global_load_dwordx4 v[40:43], v98, s[0:1] nt
	global_load_dwordx4 v[44:47], v99, s[0:1] nt
	global_load_dwordx4 v[48:51], v100, s[0:1] nt
	global_load_dwordx4 v[52:55], v101, s[0:1] nt
	global_load_dwordx4 v[56:59], v102, s[0:1] nt
	global_load_dwordx4 v[60:63], v103, s[0:1] nt
	s_cmp_ge_u32 s8, 0x200
	s_cbranch_scc1 .Ltail_two
; #define LAS __attribute__((address_space(3)))
; __device__ __forceinline__ void transpose_item_fp8(const float* W, int N, unsigned char* W8, int pitch, int kofs, int k0, int n_src, int n_dst, float scale, LAS float* scr, int lane) {
;     const int r8 = lane >> 3, c4 = lane & 7;
;     f32x4 v[8];
; #pragma unroll
;     for (int i = 0; i < 8; ++i) v[i] = *(const f32x4*)(W + (size_t)(k0 + r8 + 8 * i) * N + n_src + 4 * c4);
; #pragma unroll
;     for (int i = 0; i < 8; ++i) { LAS float* d = scr + (r8 + 8 * i) * 33 + 4 * c4; d[0] = v[i][0]; d[1] = v[i][1]; d[2] = v[i][2]; d[3] = v[i][3]; }
;     asm volatile("s_waitcnt lgkmcnt(0)" ::: "memory");
;     const int n = lane & 31, cp = lane >> 5;
; #pragma unroll
;     for (int q = 0; q < 2; ++q) { const int ck = (2 * cp + q) * 16; const LAS float* sp = scr + ck * 33 + n; u32x4 o;
; #pragma unroll
;         for (int w = 0; w < 4; ++w) o[w] = pack_fp8x4(sp[(4 * w) * 33] * scale, sp[(4 * w + 1) * 33] * scale, sp[(4 * w + 2) * 33] * scale, sp[(4 * w + 3) * 33] * scale);
;         *(u32x4*)(W8 + (size_t)(n_dst + n) * pitch + kofs + k0 + ck) = o; }
	s_add_u32 s9, s8, 0xc00
	s_sub_u32 s4, s9, 0x400
	s_sub_u32 s5, s9, 0x600
	s_mov_b32 vcc_lo, 0x6e00400
	s_mov_b32 vcc_hi, 0x7400000
	s_cmp_lt_u32 s9, 0x600
	s_cselect_b32 s5, s4, s5
	s_cselect_b32 s0, s14, s10
	s_cselect_b32 s1, s15, s11
	s_cselect_b32 s100, vcc_lo, vcc_hi
	s_movk_i32 s4, 0x600
	s_movk_i32 vcc_lo, 0x800
	s_cselect_b32 s4, s4, vcc_lo
	s_mov_b32 vcc_hi, 0x6e00000
	s_cmp_lt_u32 s9, 0x400
	s_cselect_b32 s5, s9, s5
	s_cselect_b32 s0, s12, s0
	s_cselect_b32 s1, s13, s1
	s_cselect_b32 s100, vcc_hi, s100
	s_lshr_b32 s9, s5, 6
	s_and_b32 s5, s5, 63
	s_lshl_b32 vcc_lo, s9, 19
	s_lshl_b32 vcc_hi, s5, 7
	s_add_u32 vcc_lo, vcc_lo, vcc_hi
	s_add_u32 s0, s0, vcc_lo
	s_addc_u32 s1, s1, 0
	s_lshl_b32 s5, s5, 5
	s_mul_i32 s5, s5, s4
	s_lshl_b32 s9, s9, 6
	s_add_u32 s100, s100, s5
	s_add_u32 s100, s100, s9
	v_mov_b32_e32 v113, s4
	v_mad_u32_u24 v124, v104, v113, v108
	v_mad_u32_u24 v125, v105, v113, v108
	v_mad_u32_u24 v126, v106, v113, v108
	v_mad_u32_u24 v127, v107, v113, v108
	v_add_u32_e32 v124, s100, v124
	v_add_u32_e32 v125, s100, v125
	v_add_u32_e32 v126, s100, v126
	v_add_u32_e32 v127, s100, v127
	global_load_dwordx4 v[64:67], v96, s[0:1] nt
	global_load_dwordx4 v[68:71], v97, s[0:1] nt
	global_load_dwordx4 v[72:75], v98, s[0:1] nt
	global_load_dwordx4 v[76:79], v99, s[0:1] nt
	global_load_dwordx4 v[80:83], v100, s[0:1] nt
	global_load_dwordx4 v[84:87], v101, s[0:1] nt
	global_load_dwordx4 v[88:91], v102, s[0:1] nt
	global_load_dwordx4 v[92:95], v103, s[0:1] nt
	s_mov_b32 s4, 0x42800000
	s_mov_b32 s5, 0x42800000
	s_waitcnt vmcnt(16)
	v_pk_mul_f32 v[0:1], v[0:1], s[4:5]
	v_pk_mul_f32 v[2:3], v[2:3], s[4:5]
	v_pk_mul_f32 v[4:5], v[4:5], s[4:5]
	v_pk_mul_f32 v[6:7], v[6:7], s[4:5]
	v_pk_mul_f32 v[8:9], v[8:9], s[4:5]
	v_pk_mul_f32 v[10:11], v[10:11], s[4:5]
	v_pk_mul_f32 v[12:13], v[12:13], s[4:5]
	v_pk_mul_f32 v[14:15], v[14:15], s[4:5]
	v_pk_mul_f32 v[16:17], v[16:17], s[4:5]
	v_pk_mul_f32 v[18:19], v[18:19], s[4:5]
	v_pk_mul_f32 v[20:21], v[20:21], s[4:5]
	v_pk_mul_f32 v[22:23], v[22:23], s[4:5]
	v_pk_mul_f32 v[24:25], v[24:25], s[4:5]
	v_pk_mul_f32 v[26:27], v[26:27], s[4:5]
	v_pk_mul_f32 v[28:29], v[28:29], s[4:5]
	v_pk_mul_f32 v[30:31], v[30:31], s[4:5]
	v_cvt_pk_fp8_f32 v109, v0, v4
	v_cvt_pk_fp8_f32 v110, v8, v12
	v_cvt_pk_fp8_f32 v111, v16, v20
	v_cvt_pk_fp8_f32 v112, v24, v28
	v_and_b32_e32 v109, 0xffff, v109
	v_and_b32_e32 v111, 0xffff, v111
	v_lshl_or_b32 v128, v110, 16, v109
	v_lshl_or_b32 v129, v112, 16, v111
	global_store_dwordx2 v116, v[128:129], s[90:91]
	v_cvt_pk_fp8_f32 v109, v1, v5
	v_cvt_pk_fp8_f32 v110, v9, v13
	v_cvt_pk_fp8_f32 v111, v17, v21
	v_cvt_pk_fp8_f32 v112, v25, v29
	v_and_b32_e32 v109, 0xffff, v109
	v_and_b32_e32 v111, 0xffff, v111
	v_lshl_or_b32 v130, v110, 16, v109
	v_lshl_or_b32 v131, v112, 16, v111
	global_store_dwordx2 v117, v[130:131], s[90:91]
	v_cvt_pk_fp8_f32 v109, v2, v6
	v_cvt_pk_fp8_f32 v110, v10, v14
	v_cvt_pk_fp8_f32 v111, v18, v22
	v_cvt_pk_fp8_f32 v112, v26, v30
	v_and_b32_e32 v109, 0xffff, v109
	v_and_b32_e32 v111, 0xffff, v111
	v_lshl_or_b32 v128, v110, 16, v109
	v_lshl_or_b32 v129, v112, 16, v111
	global_store_dwordx2 v118, v[128:129], s[90:91]
	v_cvt_pk_fp8_f32 v109, v3, v7
	v_cvt_pk_fp8_f32 v110, v11, v15
	v_cvt_pk_fp8_f32 v111, v19, v23
	v_cvt_pk_fp8_f32 v112, v27, v31
	v_and_b32_e32 v109, 0xffff, v109
	v_and_b32_e32 v111, 0xffff, v111
	v_lshl_or_b32 v130, v110, 16, v109
	v_lshl_or_b32 v131, v112, 16, v111
	global_store_dwordx2 v119, v[130:131], s[90:91]
	s_waitcnt vmcnt(12)
; #define LAS __attribute__((address_space(3)))
; __device__ __forceinline__ void transpose_item_fp8(const float* W, int N, unsigned char* W8, int pitch, int kofs, int k0, int n_src, int n_dst, float scale, LAS float* scr, int lane) {
;     ...
;     const int n = lane & 31, cp = lane >> 5;
; #pragma unroll
;     for (int q = 0; q < 2; ++q) { const int ck = (2 * cp + q) * 16; const LAS float* sp = scr + ck * 33 + n; u32x4 o;
; #pragma unroll
;         for (int w = 0; w < 4; ++w) o[w] = pack_fp8x4(sp[(4 * w) * 33] * scale, sp[(4 * w + 1) * 33] * scale, sp[(4 * w + 2) * 33] * scale, sp[(4 * w + 3) * 33] * scale);
;         *(u32x4*)(W8 + (size_t)(n_dst + n) * pitch + kofs + k0 + ck) = o; }
	v_pk_mul_f32 v[32:33], v[32:33], s[4:5]
	v_pk_mul_f32 v[34:35], v[34:35], s[4:5]
	v_pk_mul_f32 v[36:37], v[36:37], s[4:5]
	v_pk_mul_f32 v[38:39], v[38:39], s[4:5]
	v_pk_mul_f32 v[40:41], v[40:41], s[4:5]
	v_pk_mul_f32 v[42:43], v[42:43], s[4:5]
	v_pk_mul_f32 v[44:45], v[44:45], s[4:5]
	v_pk_mul_f32 v[46:47], v[46:47], s[4:5]
	v_pk_mul_f32 v[48:49], v[48:49], s[4:5]
	v_pk_mul_f32 v[50:51], v[50:51], s[4:5]
	v_pk_mul_f32 v[52:53], v[52:53], s[4:5]
	v_pk_mul_f32 v[54:55], v[54:55], s[4:5]
	v_pk_mul_f32 v[56:57], v[56:57], s[4:5]
	v_pk_mul_f32 v[58:59], v[58:59], s[4:5]
	v_pk_mul_f32 v[60:61], v[60:61], s[4:5]
	v_pk_mul_f32 v[62:63], v[62:63], s[4:5]
	v_cvt_pk_fp8_f32 v109, v32, v36
	v_cvt_pk_fp8_f32 v110, v40, v44
	v_cvt_pk_fp8_f32 v111, v48, v52
	v_cvt_pk_fp8_f32 v112, v56, v60
	v_and_b32_e32 v109, 0xffff, v109
	v_and_b32_e32 v111, 0xffff, v111
	v_lshl_or_b32 v128, v110, 16, v109
	v_lshl_or_b32 v129, v112, 16, v111
	global_store_dwordx2 v120, v[128:129], s[90:91]
	v_cvt_pk_fp8_f32 v109, v33, v37
	v_cvt_pk_fp8_f32 v110, v41, v45
	v_cvt_pk_fp8_f32 v111, v49, v53
	v_cvt_pk_fp8_f32 v112, v57, v61
	v_and_b32_e32 v109, 0xffff, v109
	v_and_b32_e32 v111, 0xffff, v111
	v_lshl_or_b32 v130, v110, 16, v109
	v_lshl_or_b32 v131, v112, 16, v111
	global_store_dwordx2 v121, v[130:131], s[90:91]
	v_cvt_pk_fp8_f32 v109, v34, v38
	v_cvt_pk_fp8_f32 v110, v42, v46
	v_cvt_pk_fp8_f32 v111, v50, v54
	v_cvt_pk_fp8_f32 v112, v58, v62
	v_and_b32_e32 v109, 0xffff, v109
	v_and_b32_e32 v111, 0xffff, v111
	v_lshl_or_b32 v128, v110, 16, v109
	v_lshl_or_b32 v129, v112, 16, v111
	global_store_dwordx2 v122, v[128:129], s[90:91]
	v_cvt_pk_fp8_f32 v109, v35, v39
	v_cvt_pk_fp8_f32 v110, v43, v47
	v_cvt_pk_fp8_f32 v111, v51, v55
	v_cvt_pk_fp8_f32 v112, v59, v63
	v_and_b32_e32 v109, 0xffff, v109
	v_and_b32_e32 v111, 0xffff, v111
	v_lshl_or_b32 v130, v110, 16, v109
	v_lshl_or_b32 v131, v112, 16, v111
	global_store_dwordx2 v123, v[130:131], s[90:91]
	s_waitcnt vmcnt(8)
	v_pk_mul_f32 v[64:65], v[64:65], s[4:5]
	v_pk_mul_f32 v[66:67], v[66:67], s[4:5]
	v_pk_mul_f32 v[68:69], v[68:69], s[4:5]
	v_pk_mul_f32 v[70:71], v[70:71], s[4:5]
	v_pk_mul_f32 v[72:73], v[72:73], s[4:5]
	v_pk_mul_f32 v[74:75], v[74:75], s[4:5]
	v_pk_mul_f32 v[76:77], v[76:77], s[4:5]
	v_pk_mul_f32 v[78:79], v[78:79], s[4:5]
	v_pk_mul_f32 v[80:81], v[80:81], s[4:5]
	v_pk_mul_f32 v[82:83], v[82:83], s[4:5]
	v_pk_mul_f32 v[84:85], v[84:85], s[4:5]
	v_pk_mul_f32 v[86:87], v[86:87], s[4:5]
	v_pk_mul_f32 v[88:89], v[88:89], s[4:5]
	v_pk_mul_f32 v[90:91], v[90:91], s[4:5]
	v_pk_mul_f32 v[92:93], v[92:93], s[4:5]
	v_pk_mul_f32 v[94:95], v[94:95], s[4:5]
	v_cvt_pk_fp8_f32 v109, v64, v68
	v_cvt_pk_fp8_f32 v110, v72, v76
	v_cvt_pk_fp8_f32 v111, v80, v84
	v_cvt_pk_fp8_f32 v112, v88, v92
	v_and_b32_e32 v109, 0xffff, v109
	v_and_b32_e32 v111, 0xffff, v111
	v_lshl_or_b32 v128, v110, 16, v109
	v_lshl_or_b32 v129, v112, 16, v111
	global_store_dwordx2 v124, v[128:129], s[90:91]
	v_cvt_pk_fp8_f32 v109, v65, v69
	v_cvt_pk_fp8_f32 v110, v73, v77
	v_cvt_pk_fp8_f32 v111, v81, v85
	v_cvt_pk_fp8_f32 v112, v89, v93
	v_and_b32_e32 v109, 0xffff, v109
	v_and_b32_e32 v111, 0xffff, v111
	v_lshl_or_b32 v130, v110, 16, v109
	v_lshl_or_b32 v131, v112, 16, v111
	global_store_dwordx2 v125, v[130:131], s[90:91]
	v_cvt_pk_fp8_f32 v109, v66, v70
	v_cvt_pk_fp8_f32 v110, v74, v78
	v_cvt_pk_fp8_f32 v111, v82, v86
	v_cvt_pk_fp8_f32 v112, v90, v94
	v_and_b32_e32 v109, 0xffff, v109
	v_and_b32_e32 v111, 0xffff, v111
	v_lshl_or_b32 v128, v110, 16, v109
	v_lshl_or_b32 v129, v112, 16, v111
	global_store_dwordx2 v126, v[128:129], s[90:91]
	v_cvt_pk_fp8_f32 v109, v67, v71
	v_cvt_pk_fp8_f32 v110, v75, v79
	v_cvt_pk_fp8_f32 v111, v83, v87
	v_cvt_pk_fp8_f32 v112, v91, v95
	v_and_b32_e32 v109, 0xffff, v109
	v_and_b32_e32 v111, 0xffff, v111
	v_lshl_or_b32 v130, v110, 16, v109
	v_lshl_or_b32 v131, v112, 16, v111
	global_store_dwordx2 v127, v[130:131], s[90:91]
	s_branch .LBB0_279

; __device__ __forceinline__ void own_barrier(unsigned* cnt, unsigned G) {
;     ...
;         unsigned spins = 0;
;         while (__hip_atomic_load(cnt, __ATOMIC_RELAXED, __HIP_MEMORY_SCOPE_AGENT) < target && ++spins < (1u << 22)) __builtin_amdgcn_s_sleep(1);
;         __builtin_amdgcn_fence(__ATOMIC_ACQUIRE, "agent"); asm volatile("s_waitcnt vmcnt(0)" ::: "memory");
.Lseam1_pollonly:
	s_lshl_b32 s100, s2, 12
	s_add_u32 s100, s100, 0x8e10000
	v_mov_b32_e32 v1, s100
	s_branch .Lseam1_wait
